# GEMM1 epilogue: bf16 tile staged through LDS and stored as coalesced 16-byte rows (was 8-byte scattered write-through stores)
# speedup vs baseline: 1.0736x; 1.0614x over previous
.LBB0_304:
	s_mov_b32 s0, s38
	s_add_i32 s56, s56, 1
	s_add_i32 s38, s38, s39
	s_cmp_lt_u32 s56, s71
	s_cselect_b32 s58, s38, s0
	s_waitcnt vmcnt(8)
	v_mad_i64_i32 v[54:55], s[0:1], s58, v137, v[4:5]
	s_mov_b32 s69, s77
	v_lshl_add_u64 v[56:57], v[54:55], 0, s[76:77]
	v_lshl_add_u64 v[58:59], v[54:55], 0, s[68:69]
	v_lshl_add_u64 v[54:55], v[54:55], 0, s[98:99]
	global_load_dwordx4 v[86:89], v[56:57], off
	global_load_dwordx4 v[82:85], v[58:59], off
	v_lshl_add_u64 v[56:57], v[54:55], 0, s[76:77]
	v_lshl_add_u64 v[54:55], v[54:55], 0, s[68:69]
	global_load_dwordx4 v[78:81], v[56:57], off
	global_load_dwordx4 v[74:77], v[54:55], off
	v_mad_i64_i32 v[54:55], s[0:1], s58, v137, v[112:113]
	v_add_co_u32_e32 v56, vcc, 0x1000, v54
	s_nop 1
	v_addc_co_u32_e32 v57, vcc, 0, v55, vcc
	global_load_dwordx4 v[66:69], v[54:55], off
	global_load_dwordx4 v[58:61], v[54:55], off offset:128
	global_load_dwordx4 v[70:73], v[56:57], off offset:2112
	global_load_dwordx4 v[62:65], v[56:57], off offset:2240
	v_mad_i64_i32 v[54:55], s[0:1], s58, v137, v[114:115]
	global_load_dwordx4 v[54:57], v[54:55], off
	s_and_b64 vcc, exec, s[4:5]
	s_cbranch_vccnz .LBB0_314
	v_add3_u32 v98, v107, v186, 16
	v_add3_u32 v99, v107, v187, 16
	v_add3_u32 v100, v107, v190, 16
	v_add3_u32 v101, v107, v191, 16
	v_add3_u32 v102, v107, v194, 16
	v_add3_u32 v103, v107, v195, 16
	v_add3_u32 v104, v107, v198, 16
	v_add3_u32 v105, v107, v199, 16
	ds_read2st64_b32 v[220:221], v165 offset1:1
	ds_read2st64_b32 v[222:223], v165 offset0:2 offset1:3
	ds_read_u16 v236, v98
	ds_read_u16 v237, v98 offset:8192
	ds_read_u16 v238, v98 offset:128
	ds_read_u16 v239, v98 offset:8320
	ds_read_u16 v240, v99 offset:256
	ds_read_u16 v241, v99 offset:8448
	ds_read_u16 v242, v99 offset:384
	ds_read_u16 v243, v99 offset:8576
	s_waitcnt lgkmcnt(0)
	ds_read2st64_b32 v[224:225], v188 offset1:1
	ds_read2st64_b32 v[226:227], v188 offset0:2 offset1:3
	ds_read_u16 v244, v100
	ds_read_u16 v245, v100 offset:8192
	ds_read_u16 v246, v100 offset:128
	ds_read_u16 v247, v100 offset:8320
	ds_read_u16 v248, v101 offset:256
	ds_read_u16 v249, v101 offset:8448
	ds_read_u16 v250, v101 offset:384
	ds_read_u16 v251, v101 offset:8576
	v_add_f32_e32 v2, v220, v221
	v_add_f32_e32 v2, v2, v222
	v_add_f32_e32 v253, v2, v223
	v_mul_f32_e32 v223, 0x3fb8aa3b, v253
	v_exp_f32_e32 v223, v223
	v_cndmask_b32_e64 v2, 0, v220, s[18:19]
	v_cndmask_b32_e64 v220, 0, v221, s[14:15]
	v_add_f32_e32 v2, v2, v220
	v_cndmask_b32_e64 v220, 0, v222, s[20:21]
	v_add_f32_e32 v2, v2, v220
	v_add_f32_e32 v220, v95, v2
	v_sub_f32_e32 v221, v253, v220
	v_add_f32_e32 v2, v91, v220
	v_cndmask_b32_e64 v95, v221, v2, s[2:3]
	v_sub_f32_e32 v2, v221, v91
	v_add_f32_e32 v253, v94, v220
	v_cndmask_b32_e64 v91, v2, v253, s[2:3]
	v_sub_f32_e32 v2, v221, v94
	v_add_f32_e32 v253, v93, v220
	v_cndmask_b32_e64 v94, v2, v253, s[2:3]
	v_sub_f32_e32 v2, v221, v93
	v_add_f32_e32 v253, v92, v220
	v_cndmask_b32_e64 v93, v2, v253, s[2:3]
	v_mul_f32_e32 v95, 0x3fb8aa3b, v95
	v_mul_f32_e32 v91, 0x3fb8aa3b, v91
	v_mul_f32_e32 v94, 0x3fb8aa3b, v94
	v_mul_f32_e32 v93, 0x3fb8aa3b, v93
	v_exp_f32_e32 v95, v95
	v_exp_f32_e32 v91, v91
	v_exp_f32_e32 v94, v94
	v_exp_f32_e32 v93, v93
	v_rcp_f32_e32 v92, v95
	v_rcp_f32_e32 v220, v91
	v_rcp_f32_e32 v221, v94
	v_rcp_f32_e32 v222, v93
	s_waitcnt lgkmcnt(0)
	s_and_saveexec_b64 s[0:1], s[82:83]
	ds_write_b32 v185, v223
	s_or_b64 exec, exec, s[0:1]
	v_lshlrev_b32_e32 v2, 16, v236
	v_lshlrev_b32_e32 v253, 16, v237
	v_mul_f32_e32 v2, v95, v2
	v_mul_f32_e32 v253, v92, v253
	v_cvt_pk_bf16_f32 v236, v2, v253
	ds_write_b16 v98, v236
	ds_write_b16_d16_hi v98, v236 offset:8192
	v_mul_f32_e32 v95, v223, v253
	v_lshlrev_b32_e32 v2, 16, v238
	v_lshlrev_b32_e32 v253, 16, v239
	v_mul_f32_e32 v2, v91, v2
	v_mul_f32_e32 v253, v220, v253
	v_cvt_pk_bf16_f32 v238, v2, v253
	ds_write_b16 v98, v238 offset:128
	ds_write_b16_d16_hi v98, v238 offset:8320
	v_mul_f32_e32 v91, v223, v253
	v_lshlrev_b32_e32 v2, 16, v240
	v_lshlrev_b32_e32 v253, 16, v241
	v_mul_f32_e32 v2, v94, v2
	v_mul_f32_e32 v253, v221, v253
	v_cvt_pk_bf16_f32 v240, v2, v253
	ds_write_b16 v99, v240 offset:256
	ds_write_b16_d16_hi v99, v240 offset:8448
	v_mul_f32_e32 v94, v223, v253
	v_lshlrev_b32_e32 v2, 16, v242
	v_lshlrev_b32_e32 v253, 16, v243
	v_mul_f32_e32 v2, v93, v2
	v_mul_f32_e32 v253, v222, v253
	v_cvt_pk_bf16_f32 v242, v2, v253
	ds_write_b16 v99, v242 offset:384
	ds_write_b16_d16_hi v99, v242 offset:8576
	v_mul_f32_e32 v93, v223, v253
	v_cvt_pk_bf16_f32 v236, v95, v91
	v_cvt_pk_bf16_f32 v237, v94, v93
	v_add_u32_e32 v252, v182, v144
	ds_write_b64 v252, v[236:237] offset:16384
	s_waitcnt lgkmcnt(5)
	ds_read2st64_b32 v[228:229], v192 offset1:1
	ds_read2st64_b32 v[230:231], v192 offset0:2 offset1:3
	ds_read_u16 v236, v102
	ds_read_u16 v237, v102 offset:8192
	ds_read_u16 v238, v102 offset:128
	ds_read_u16 v239, v102 offset:8320
	ds_read_u16 v240, v103 offset:256
	ds_read_u16 v241, v103 offset:8448
	ds_read_u16 v242, v103 offset:384
	ds_read_u16 v243, v103 offset:8576
	v_add_f32_e32 v2, v224, v225
	v_add_f32_e32 v2, v2, v226
	v_add_f32_e32 v253, v2, v227
	v_mul_f32_e32 v227, 0x3fb8aa3b, v253
	v_exp_f32_e32 v227, v227
	v_cndmask_b32_e64 v2, 0, v224, s[18:19]
	v_cndmask_b32_e64 v224, 0, v225, s[14:15]
	v_add_f32_e32 v2, v2, v224
	v_cndmask_b32_e64 v224, 0, v226, s[20:21]
	v_add_f32_e32 v2, v2, v224
	v_add_f32_e32 v224, v211, v2
	v_sub_f32_e32 v225, v253, v224
	v_add_f32_e32 v2, v90, v224
	v_cndmask_b32_e64 v211, v225, v2, s[2:3]
	v_sub_f32_e32 v2, v225, v90
	v_add_f32_e32 v253, v210, v224
	v_cndmask_b32_e64 v90, v2, v253, s[2:3]
	v_sub_f32_e32 v2, v225, v210
	v_add_f32_e32 v253, v135, v224
	v_cndmask_b32_e64 v210, v2, v253, s[2:3]
	v_sub_f32_e32 v2, v225, v135
	v_add_f32_e32 v253, v209, v224
	v_cndmask_b32_e64 v135, v2, v253, s[2:3]
	v_mul_f32_e32 v211, 0x3fb8aa3b, v211
	v_mul_f32_e32 v90, 0x3fb8aa3b, v90
	v_mul_f32_e32 v210, 0x3fb8aa3b, v210
	v_mul_f32_e32 v135, 0x3fb8aa3b, v135
	v_exp_f32_e32 v211, v211
	v_exp_f32_e32 v90, v90
	v_exp_f32_e32 v210, v210
	v_exp_f32_e32 v135, v135
	v_rcp_f32_e32 v209, v211
	v_rcp_f32_e32 v224, v90
	v_rcp_f32_e32 v225, v210
	v_rcp_f32_e32 v226, v135
	s_waitcnt lgkmcnt(0)
	s_and_saveexec_b64 s[0:1], s[82:83]
	ds_write_b32 v189, v227
	s_or_b64 exec, exec, s[0:1]
	v_lshlrev_b32_e32 v2, 16, v244
	v_lshlrev_b32_e32 v253, 16, v245
	v_mul_f32_e32 v2, v211, v2
	v_mul_f32_e32 v253, v209, v253
	v_cvt_pk_bf16_f32 v244, v2, v253
	ds_write_b16 v100, v244
	ds_write_b16_d16_hi v100, v244 offset:8192
	v_mul_f32_e32 v211, v227, v253
	v_lshlrev_b32_e32 v2, 16, v246
	v_lshlrev_b32_e32 v253, 16, v247
	v_mul_f32_e32 v2, v90, v2
	v_mul_f32_e32 v253, v224, v253
	v_cvt_pk_bf16_f32 v246, v2, v253
	ds_write_b16 v100, v246 offset:128
	ds_write_b16_d16_hi v100, v246 offset:8320
	v_mul_f32_e32 v90, v227, v253
	v_lshlrev_b32_e32 v2, 16, v248
	v_lshlrev_b32_e32 v253, 16, v249
	v_mul_f32_e32 v2, v210, v2
	v_mul_f32_e32 v253, v225, v253
	v_cvt_pk_bf16_f32 v248, v2, v253
	ds_write_b16 v101, v248 offset:256
	ds_write_b16_d16_hi v101, v248 offset:8448
	v_mul_f32_e32 v210, v227, v253
	v_lshlrev_b32_e32 v2, 16, v250
	v_lshlrev_b32_e32 v253, 16, v251
	v_mul_f32_e32 v2, v135, v2
	v_mul_f32_e32 v253, v226, v253
	v_cvt_pk_bf16_f32 v250, v2, v253
	ds_write_b16 v101, v250 offset:384
	ds_write_b16_d16_hi v101, v250 offset:8576
	v_mul_f32_e32 v135, v227, v253
	v_cvt_pk_bf16_f32 v244, v211, v90
	v_cvt_pk_bf16_f32 v245, v210, v135
	ds_write_b64 v203, v[244:245] offset:16384
	s_waitcnt lgkmcnt(5)
	ds_read2st64_b32 v[232:233], v196 offset1:1
	ds_read2st64_b32 v[234:235], v196 offset0:2 offset1:3
	ds_read_u16 v244, v104
	ds_read_u16 v245, v104 offset:8192
	ds_read_u16 v246, v104 offset:128
	ds_read_u16 v247, v104 offset:8320
	ds_read_u16 v248, v105 offset:256
	ds_read_u16 v249, v105 offset:8448
	ds_read_u16 v250, v105 offset:384
	ds_read_u16 v251, v105 offset:8576
	v_add_f32_e32 v2, v228, v229
	v_add_f32_e32 v2, v2, v230
	v_add_f32_e32 v253, v2, v231
	v_mul_f32_e32 v231, 0x3fb8aa3b, v253
	v_exp_f32_e32 v231, v231
	v_cndmask_b32_e64 v2, 0, v228, s[18:19]
	v_cndmask_b32_e64 v228, 0, v229, s[14:15]
	v_add_f32_e32 v2, v2, v228
	v_cndmask_b32_e64 v228, 0, v230, s[20:21]
	v_add_f32_e32 v2, v2, v228
	v_add_f32_e32 v228, v215, v2
	v_sub_f32_e32 v229, v253, v228
	v_add_f32_e32 v2, v97, v228
	v_cndmask_b32_e64 v215, v229, v2, s[2:3]
	v_sub_f32_e32 v2, v229, v97
	v_add_f32_e32 v253, v214, v228
	v_cndmask_b32_e64 v97, v2, v253, s[2:3]
	v_sub_f32_e32 v2, v229, v214
	v_add_f32_e32 v253, v212, v228
	v_cndmask_b32_e64 v214, v2, v253, s[2:3]
	v_sub_f32_e32 v2, v229, v212
	v_add_f32_e32 v253, v213, v228
	v_cndmask_b32_e64 v212, v2, v253, s[2:3]
	v_mul_f32_e32 v215, 0x3fb8aa3b, v215
	v_mul_f32_e32 v97, 0x3fb8aa3b, v97
	v_mul_f32_e32 v214, 0x3fb8aa3b, v214
	v_mul_f32_e32 v212, 0x3fb8aa3b, v212
	v_exp_f32_e32 v215, v215
	v_exp_f32_e32 v97, v97
	v_exp_f32_e32 v214, v214
	v_exp_f32_e32 v212, v212
	v_rcp_f32_e32 v213, v215
	v_rcp_f32_e32 v228, v97
	v_rcp_f32_e32 v229, v214
	v_rcp_f32_e32 v230, v212
	s_waitcnt lgkmcnt(0)
	s_and_saveexec_b64 s[0:1], s[82:83]
	ds_write_b32 v193, v231
	s_or_b64 exec, exec, s[0:1]
	v_lshlrev_b32_e32 v2, 16, v236
	v_lshlrev_b32_e32 v253, 16, v237
	v_mul_f32_e32 v2, v215, v2
	v_mul_f32_e32 v253, v213, v253
	v_cvt_pk_bf16_f32 v236, v2, v253
	ds_write_b16 v102, v236
	ds_write_b16_d16_hi v102, v236 offset:8192
	v_mul_f32_e32 v215, v231, v253
	v_lshlrev_b32_e32 v2, 16, v238
	v_lshlrev_b32_e32 v253, 16, v239
	v_mul_f32_e32 v2, v97, v2
	v_mul_f32_e32 v253, v228, v253
	v_cvt_pk_bf16_f32 v238, v2, v253
	ds_write_b16 v102, v238 offset:128
	ds_write_b16_d16_hi v102, v238 offset:8320
	v_mul_f32_e32 v97, v231, v253
	v_lshlrev_b32_e32 v2, 16, v240
	v_lshlrev_b32_e32 v253, 16, v241
	v_mul_f32_e32 v2, v214, v2
	v_mul_f32_e32 v253, v229, v253
	v_cvt_pk_bf16_f32 v240, v2, v253
	ds_write_b16 v103, v240 offset:256
	ds_write_b16_d16_hi v103, v240 offset:8448
	v_mul_f32_e32 v214, v231, v253
	v_lshlrev_b32_e32 v2, 16, v242
	v_lshlrev_b32_e32 v253, 16, v243
	v_mul_f32_e32 v2, v212, v2
	v_mul_f32_e32 v253, v230, v253
	v_cvt_pk_bf16_f32 v242, v2, v253
	ds_write_b16 v103, v242 offset:384
	ds_write_b16_d16_hi v103, v242 offset:8576
	v_mul_f32_e32 v212, v231, v253
	v_cvt_pk_bf16_f32 v236, v215, v97
	v_cvt_pk_bf16_f32 v237, v214, v212
	ds_write_b64 v204, v[236:237] offset:16384
	v_add_f32_e32 v2, v232, v233
	v_add_f32_e32 v2, v2, v234
	v_add_f32_e32 v253, v2, v235
	v_mul_f32_e32 v235, 0x3fb8aa3b, v253
	v_exp_f32_e32 v235, v235
	v_cndmask_b32_e64 v2, 0, v232, s[18:19]
	v_cndmask_b32_e64 v232, 0, v233, s[14:15]
	v_add_f32_e32 v2, v2, v232
	v_cndmask_b32_e64 v232, 0, v234, s[20:21]
	v_add_f32_e32 v2, v2, v232
	v_add_f32_e32 v232, v219, v2
	v_sub_f32_e32 v233, v253, v232
	v_add_f32_e32 v2, v96, v232
	v_cndmask_b32_e64 v219, v233, v2, s[2:3]
	v_sub_f32_e32 v2, v233, v96
	v_add_f32_e32 v253, v218, v232
	v_cndmask_b32_e64 v96, v2, v253, s[2:3]
	v_sub_f32_e32 v2, v233, v218
	v_add_f32_e32 v253, v216, v232
	v_cndmask_b32_e64 v218, v2, v253, s[2:3]
	v_sub_f32_e32 v2, v233, v216
	v_add_f32_e32 v253, v217, v232
	v_cndmask_b32_e64 v216, v2, v253, s[2:3]
	v_mul_f32_e32 v219, 0x3fb8aa3b, v219
	v_mul_f32_e32 v96, 0x3fb8aa3b, v96
	v_mul_f32_e32 v218, 0x3fb8aa3b, v218
	v_mul_f32_e32 v216, 0x3fb8aa3b, v216
	v_exp_f32_e32 v219, v219
	v_exp_f32_e32 v96, v96
	v_exp_f32_e32 v218, v218
	v_exp_f32_e32 v216, v216
	v_rcp_f32_e32 v217, v219
	v_rcp_f32_e32 v232, v96
	v_rcp_f32_e32 v233, v218
	v_rcp_f32_e32 v234, v216
	s_waitcnt lgkmcnt(0)
	s_and_saveexec_b64 s[0:1], s[82:83]
	ds_write_b32 v197, v235
	s_or_b64 exec, exec, s[0:1]
	v_lshlrev_b32_e32 v2, 16, v244
	v_lshlrev_b32_e32 v253, 16, v245
	v_mul_f32_e32 v2, v219, v2
	v_mul_f32_e32 v253, v217, v253
	v_cvt_pk_bf16_f32 v244, v2, v253
	ds_write_b16 v104, v244
	ds_write_b16_d16_hi v104, v244 offset:8192
	v_mul_f32_e32 v219, v235, v253
	v_lshlrev_b32_e32 v2, 16, v246
	v_lshlrev_b32_e32 v253, 16, v247
	v_mul_f32_e32 v2, v96, v2
	v_mul_f32_e32 v253, v232, v253
	v_cvt_pk_bf16_f32 v246, v2, v253
	ds_write_b16 v104, v246 offset:128
	ds_write_b16_d16_hi v104, v246 offset:8320
	v_mul_f32_e32 v96, v235, v253
	v_lshlrev_b32_e32 v2, 16, v248
	v_lshlrev_b32_e32 v253, 16, v249
	v_mul_f32_e32 v2, v218, v2
	v_mul_f32_e32 v253, v233, v253
	v_cvt_pk_bf16_f32 v248, v2, v253
	ds_write_b16 v105, v248 offset:256
	ds_write_b16_d16_hi v105, v248 offset:8448
	v_mul_f32_e32 v218, v235, v253
	v_lshlrev_b32_e32 v2, 16, v250
	v_lshlrev_b32_e32 v253, 16, v251
	v_mul_f32_e32 v2, v216, v2
	v_mul_f32_e32 v253, v234, v253
	v_cvt_pk_bf16_f32 v250, v2, v253
	ds_write_b16 v105, v250 offset:384
	ds_write_b16_d16_hi v105, v250 offset:8576
	v_mul_f32_e32 v216, v235, v253
	v_cvt_pk_bf16_f32 v244, v219, v96
	v_cvt_pk_bf16_f32 v245, v218, v216
	ds_write_b64 v205, v[244:245] offset:16384
	s_waitcnt lgkmcnt(0)
	s_barrier

.LBB0_355:
	s_or_b64 exec, exec, s[2:3]
	v_lshl_or_b32 v56, v92, 6, v93
	v_lshlrev_b32_e32 v56, 8, v56
	v_lshrrev_b32_e32 v57, 3, v95
	v_bfe_u32 v58, v94, 6, 1
	v_lshl_or_b32 v57, v58, 3, v57
	v_and_b32_e32 v58, 4, v95
	v_lshl_add_u32 v56, v58, 1, v56
	v_add_u32_e32 v56, 16, v56
	v_or_b32_e32 v59, 0, v57
	v_xor_b32_e32 v59, v59, v93
	v_lshl_add_u32 v84, v59, 4, v56
	v_or_b32_e32 v59, 2, v57
	v_xor_b32_e32 v59, v59, v93
	v_lshl_add_u32 v85, v59, 4, v56
	v_or_b32_e32 v59, 4, v57
	v_xor_b32_e32 v59, v59, v93
	v_lshl_add_u32 v86, v59, 4, v56
	v_or_b32_e32 v59, 6, v57
	v_xor_b32_e32 v59, v59, v93
	v_lshl_add_u32 v87, v59, 4, v56
	v_cvt_pk_bf16_f32 v88, v60, v61
	v_cvt_pk_bf16_f32 v89, v62, v63
	ds_write_b64 v84, v[88:89]
	v_cvt_pk_bf16_f32 v90, v68, v69
	v_cvt_pk_bf16_f32 v91, v70, v71
	ds_write_b64 v84, v[90:91] offset:4096
	v_cvt_pk_bf16_f32 v88, v52, v53
	v_cvt_pk_bf16_f32 v89, v54, v55
	ds_write_b64 v84, v[88:89] offset:8192
	v_cvt_pk_bf16_f32 v90, v40, v41
	v_cvt_pk_bf16_f32 v91, v42, v43
	ds_write_b64 v84, v[90:91] offset:12288
	v_cvt_pk_bf16_f32 v88, v72, v73
	v_cvt_pk_bf16_f32 v89, v74, v75
	ds_write_b64 v85, v[88:89]
	v_cvt_pk_bf16_f32 v90, v48, v49
	v_cvt_pk_bf16_f32 v91, v50, v51
	ds_write_b64 v85, v[90:91] offset:4096
	v_cvt_pk_bf16_f32 v88, v44, v45
	v_cvt_pk_bf16_f32 v89, v46, v47
	ds_write_b64 v85, v[88:89] offset:8192
	v_cvt_pk_bf16_f32 v90, v36, v37
	v_cvt_pk_bf16_f32 v91, v38, v39
	ds_write_b64 v85, v[90:91] offset:12288
	v_cvt_pk_bf16_f32 v88, v32, v33
	v_cvt_pk_bf16_f32 v89, v34, v35
	ds_write_b64 v86, v[88:89]
	v_cvt_pk_bf16_f32 v90, v28, v29
	v_cvt_pk_bf16_f32 v91, v30, v31
	ds_write_b64 v86, v[90:91] offset:4096
	v_cvt_pk_bf16_f32 v88, v24, v25
	v_cvt_pk_bf16_f32 v89, v26, v27
	ds_write_b64 v86, v[88:89] offset:8192
	v_cvt_pk_bf16_f32 v90, v20, v21
	v_cvt_pk_bf16_f32 v91, v22, v23
	ds_write_b64 v86, v[90:91] offset:12288
	v_cvt_pk_bf16_f32 v88, v16, v17
	v_cvt_pk_bf16_f32 v89, v18, v19
	ds_write_b64 v87, v[88:89]
	v_cvt_pk_bf16_f32 v90, v12, v13
	v_cvt_pk_bf16_f32 v91, v14, v15
	ds_write_b64 v87, v[90:91] offset:4096
	v_cvt_pk_bf16_f32 v88, v8, v9
	v_cvt_pk_bf16_f32 v89, v10, v11
	ds_write_b64 v87, v[88:89] offset:8192
	v_cvt_pk_bf16_f32 v90, v4, v5
	v_cvt_pk_bf16_f32 v91, v6, v7
	ds_write_b64 v87, v[90:91] offset:12288
.LBB0_423:
	s_or_b64 exec, exec, s[0:1]
	s_waitcnt lgkmcnt(0)
	s_barrier
	v_and_b32_e32 v4, 15, v0
	v_lshrrev_b32_e32 v5, 4, v0
	v_xor_b32_e32 v6, v4, v5
	v_lshlrev_b32_e32 v6, 4, v6
	v_lshl_add_u32 v6, v5, 8, v6
	v_add_u32_e32 v6, 16, v6
	ds_read_b128 v[8:11], v6
	ds_read_b128 v[12:15], v6 offset:4096
	ds_read_b128 v[16:19], v6 offset:8192
	ds_read_b128 v[20:23], v6 offset:12288
	ds_read_b128 v[24:27], v6 offset:16384
	ds_read_b128 v[28:31], v6 offset:20480
	ds_read_b128 v[32:35], v6 offset:24576
	ds_read_b128 v[36:39], v6 offset:28672
	v_add_u32_e32 v7, s8, v5
	s_lshl_b32 s2, s64, 8
	v_lshl_add_u32 v40, v4, 4, s2
	v_mov_b32_e32 v41, 0
	v_mad_u64_u32 v[42:43], s[4:5], v7, s29, v[40:41]
	v_lshl_add_u64 v[42:43], s[50:51], 0, v[42:43]
	s_lshl_b32 s3, s64, 7
	v_lshl_add_u32 v44, v4, 3, s3
	v_cmp_gt_i32_e32 vcc, s19, v44
	s_mov_b32 s6, 0x18400
	s_and_saveexec_b64 s[4:5], vcc
	s_and_b64 vcc, exec, s[58:59]
	s_cbranch_vccz .Lepi_plain
	s_waitcnt lgkmcnt(7)
	global_store_dwordx4 v[42:43], v[8:11], off sc1
	v_add_co_u32_e32 v42, vcc, s6, v42
	s_nop 1
	v_addc_co_u32_e32 v43, vcc, 0, v43, vcc
	s_waitcnt lgkmcnt(6)
	global_store_dwordx4 v[42:43], v[12:15], off sc1
	v_add_co_u32_e32 v42, vcc, s6, v42
	s_nop 1
	v_addc_co_u32_e32 v43, vcc, 0, v43, vcc
	s_waitcnt lgkmcnt(5)
	global_store_dwordx4 v[42:43], v[16:19], off sc1
	v_add_co_u32_e32 v42, vcc, s6, v42
	s_nop 1
	v_addc_co_u32_e32 v43, vcc, 0, v43, vcc
	s_waitcnt lgkmcnt(4)
	global_store_dwordx4 v[42:43], v[20:23], off sc1
	v_add_co_u32_e32 v42, vcc, s6, v42
	s_nop 1
	v_addc_co_u32_e32 v43, vcc, 0, v43, vcc
	s_waitcnt lgkmcnt(3)
	global_store_dwordx4 v[42:43], v[24:27], off sc1
	v_add_co_u32_e32 v42, vcc, s6, v42
	s_nop 1
	v_addc_co_u32_e32 v43, vcc, 0, v43, vcc
	s_waitcnt lgkmcnt(2)
	global_store_dwordx4 v[42:43], v[28:31], off sc1
	v_add_co_u32_e32 v42, vcc, s6, v42
	s_nop 1
	v_addc_co_u32_e32 v43, vcc, 0, v43, vcc
	s_waitcnt lgkmcnt(1)
	global_store_dwordx4 v[42:43], v[32:35], off sc1
	v_add_co_u32_e32 v42, vcc, s6, v42
	s_nop 1
	v_addc_co_u32_e32 v43, vcc, 0, v43, vcc
	s_waitcnt lgkmcnt(0)
	global_store_dwordx4 v[42:43], v[36:39], off sc1
	s_branch .Lepi_done
.Lepi_plain:
	s_waitcnt lgkmcnt(7)
	global_store_dwordx4 v[42:43], v[8:11], off
	v_add_co_u32_e32 v42, vcc, s6, v42
	s_nop 1
	v_addc_co_u32_e32 v43, vcc, 0, v43, vcc
	s_waitcnt lgkmcnt(6)
	global_store_dwordx4 v[42:43], v[12:15], off
	v_add_co_u32_e32 v42, vcc, s6, v42
	s_nop 1
	v_addc_co_u32_e32 v43, vcc, 0, v43, vcc
	s_waitcnt lgkmcnt(5)
	global_store_dwordx4 v[42:43], v[16:19], off
	v_add_co_u32_e32 v42, vcc, s6, v42
	s_nop 1
	v_addc_co_u32_e32 v43, vcc, 0, v43, vcc
	s_waitcnt lgkmcnt(4)
	global_store_dwordx4 v[42:43], v[20:23], off
	v_add_co_u32_e32 v42, vcc, s6, v42
	s_nop 1
	v_addc_co_u32_e32 v43, vcc, 0, v43, vcc
	s_waitcnt lgkmcnt(3)
	global_store_dwordx4 v[42:43], v[24:27], off
	v_add_co_u32_e32 v42, vcc, s6, v42
	s_nop 1
	v_addc_co_u32_e32 v43, vcc, 0, v43, vcc
	s_waitcnt lgkmcnt(2)
	global_store_dwordx4 v[42:43], v[28:31], off
	v_add_co_u32_e32 v42, vcc, s6, v42
	s_nop 1
	v_addc_co_u32_e32 v43, vcc, 0, v43, vcc
	s_waitcnt lgkmcnt(1)
	global_store_dwordx4 v[42:43], v[32:35], off
	v_add_co_u32_e32 v42, vcc, s6, v42
	s_nop 1
	v_addc_co_u32_e32 v43, vcc, 0, v43, vcc
	s_waitcnt lgkmcnt(0)
	global_store_dwordx4 v[42:43], v[36:39], off
.Lepi_done:
	s_or_b64 exec, exec, s[4:5]
	s_xor_b64 s[0:1], s[62:63], -1
	s_andn2_b64 vcc, exec, s[0:1]
	s_cbranch_vccnz .LBB0_228
